# v26 + conv: normalize/swish loop rewritten to 8 channels per thread with one dwordx4 store per 4 tokens
# speedup vs baseline: 1.0026x; 1.0026x over previous
; #define LAS __attribute__((address_space(3)))
; __device__ __forceinline__ void conv_phase(LAS unsigned char* lds, const bf16* U, const float* state, const float* wdw, const float* bdw, const float* lng, const float* lnb, bf16* Z, int blk, int nblk, int tid) {
;     LAS unsigned* tile = (LAS unsigned*)lds;
;     typedef float f32x2 __attribute__((ext_vector_type(2)));
;     LAS f32x2* stat = (LAS f32x2*)(lds + STAT_OFF);
;     LAS f32x2* wpart = (LAS f32x2*)(lds + STAT_OFF + 256);
;     const int c0 = 2 * tid, lane = tid & 63, wave = tid >> 6;
;     f32x2 w[31];
; #pragma unroll
;     for (int k = 0; k < 31; ++k) w[k] = *(const f32x2*)(wdw + tid * 64 + 2 * k);
;     const f32x2 bd = *(const f32x2*)(bdw + c0), gg = *(const f32x2*)(lng + c0), bb = *(const f32x2*)(lnb + c0);
.LBB0_76:
.LBB0_77:
	v_readlane_b32 s0, v253, 18
	v_readlane_b32 s1, v253, 19
	s_andn2_b64 vcc, exec, s[0:1]
	s_cbranch_vccnz .LBB0_206
	v_lshlrev_b32_e32 v2, 6, v204
	v_ashrrev_i32_e32 v3, 31, v2
	v_lshl_add_u64 v[2:3], v[2:3], 2, s[70:71]
	s_mov_b64 s[0:1], 0x1a600000
	v_add_co_u32_e32 v58, vcc, 0x1a600000, v2
	v_lshl_add_u64 v[62:63], v[2:3], 0, s[0:1]
	s_nop 0
	v_addc_co_u32_e32 v59, vcc, 0, v3, vcc
	global_load_dwordx4 v[2:5], v[62:63], off offset:32
	global_load_dwordx4 v[6:9], v[62:63], off offset:16
	global_load_dwordx4 v[10:13], v[62:63], off offset:96
	global_load_dwordx4 v[14:17], v[62:63], off offset:80
	global_load_dwordx4 v[18:21], v[62:63], off offset:48
	global_load_dwordx4 v[22:25], v[62:63], off offset:64
	global_load_dwordx4 v[26:29], v[62:63], off offset:160
	global_load_dwordx4 v[30:33], v[62:63], off offset:144
	global_load_dwordx4 v[34:37], v[62:63], off offset:112
	global_load_dwordx4 v[38:41], v[62:63], off offset:128
	global_load_dwordx4 v[42:45], v[62:63], off offset:224
	global_load_dwordx4 v[46:49], v[62:63], off offset:208
	global_load_dwordx4 v[50:53], v[62:63], off offset:176
	global_load_dwordx4 v[54:57], v[62:63], off offset:192
	s_nop 0
	global_load_dwordx4 v[58:61], v[58:59], off
	s_nop 0
	global_load_dwordx2 v[66:67], v[62:63], off offset:240
	v_readlane_b32 s10, v255, 7
	v_readlane_b32 s11, v255, 8
	s_load_dwordx2 s[4:5], s[10:11], 0xc8
	s_load_dwordx2 s[8:9], s[10:11], 0x20
	s_load_dwordx4 s[0:3], s[10:11], 0xb8
	v_lshlrev_b32_e32 v62, 1, v204
	v_ashrrev_i32_e32 v63, 31, v62
	v_lshlrev_b64 v[64:65], 2, v[62:63]
	s_waitcnt lgkmcnt(0)
	v_lshl_add_u64 v[68:69], s[4:5], 0, v[64:65]
	v_lshl_add_u64 v[70:71], s[2:3], 0, v[64:65]
	v_lshl_add_u64 v[64:65], s[0:1], 0, v[64:65]
	global_load_dwordx2 v[68:69], v[68:69], off
	v_and_b32_e32 v78, 15, v204
	global_load_dwordx2 v[70:71], v[70:71], off
	v_ashrrev_i32_e32 v79, 4, v204
	global_load_dwordx2 v[72:73], v[64:65], off
	v_and_b32_e32 v226, 0x7f, v204
	v_lshlrev_b32_e32 v226, 5, v226
	v_mov_b32_e32 v227, 0
	v_lshl_add_u64 v[228:229], s[2:3], 0, v[226:227]
	global_load_dwordx4 v[210:213], v[228:229], off
	global_load_dwordx4 v[214:217], v[228:229], off offset:16
	v_lshl_add_u64 v[228:229], s[4:5], 0, v[226:227]
	s_nop 0
	global_load_dwordx4 v[218:221], v[228:229], off
	global_load_dwordx4 v[222:225], v[228:229], off offset:16
	v_cmp_eq_u32_e64 s[44:45], 0, v78
	v_lshlrev_b32_e32 v80, 8, v79
	v_lshlrev_b32_e32 v78, 3, v78
	v_readlane_b32 s0, v254, 15
	s_add_u32 s6, s70, 0x1a700000
	v_and_b32_e32 v1, 0x7f, v204
	s_waitcnt vmcnt(37)
	v_add3_u32 v144, s0, v80, v78
	v_lshlrev_b32_e32 v80, 3, v79
	v_readlane_b32 s0, v254, 16
	s_addc_u32 s7, s71, 0
	v_lshlrev_b32_e32 v76, 4, v1
	v_add_u32_e32 v145, s0, v80
	v_readlane_b32 s0, v255, 15
	v_readlane_b32 s1, v255, 16
	v_mov_b32_e32 v77, v0
	v_add_u32_e32 v81, 0x400, v204
	v_lshl_add_u64 v[78:79], v[62:63], 1, s[0:1]
	v_add_u32_e32 v63, 0x200, v204
	v_add_u32_e32 v82, 0x600, v204
	v_add_u32_e32 v83, 0x800, v204
	v_add_u32_e32 v84, 0xa00, v204
	v_add_u32_e32 v85, 0xc00, v204
	v_add_u32_e32 v86, 0xe00, v204
	v_add_u32_e32 v87, 0x1000, v204
	v_add_u32_e32 v88, 0x1200, v204
	v_add_u32_e32 v89, 0x1400, v204
	v_add_u32_e32 v90, 0x1600, v204
	v_add_u32_e32 v91, 0x1800, v204
	v_add_u32_e32 v92, 0x1a00, v204
	v_add_u32_e32 v93, 0x1c00, v204
	v_add_u32_e32 v94, 0x1e00, v204
	v_lshl_add_u64 v[74:75], s[6:7], 0, v[76:77]
	v_add_u32_e32 v65, 0, v76
	v_lshlrev_b32_e32 v76, 4, v204
	v_ashrrev_i32_e32 v146, 7, v204
	v_ashrrev_i32_e32 v147, 7, v63
	v_ashrrev_i32_e32 v148, 7, v81
	v_ashrrev_i32_e32 v149, 7, v82
	v_ashrrev_i32_e32 v150, 7, v83
	v_ashrrev_i32_e32 v151, 7, v84
	v_ashrrev_i32_e32 v152, 7, v85
	v_ashrrev_i32_e32 v153, 7, v86
	s_waitcnt vmcnt(36)
	v_ashrrev_i32_e32 v154, 7, v87
	v_ashrrev_i32_e32 v155, 7, v88
	v_ashrrev_i32_e32 v156, 7, v89
	v_ashrrev_i32_e32 v157, 7, v90
	s_waitcnt vmcnt(35)
	v_ashrrev_i32_e32 v158, 7, v91
	v_ashrrev_i32_e32 v159, 7, v92
	v_ashrrev_i32_e32 v160, 7, v93
	v_ashrrev_i32_e32 v161, 7, v94
	v_lshrrev_b32_e32 v95, 1, v204
	v_lshlrev_b32_e32 v64, 3, v1
	v_add_u32_e32 v1, 0, v76
	v_lshlrev_b32_e32 v62, 11, v146
	v_lshlrev_b32_e32 v63, 11, v147
	v_lshlrev_b32_e32 v81, 11, v148
	v_lshlrev_b32_e32 v82, 11, v149
	v_lshlrev_b32_e32 v83, 11, v150
	v_lshlrev_b32_e32 v84, 11, v151
	v_lshlrev_b32_e32 v85, 11, v152
	v_lshlrev_b32_e32 v86, 11, v153
	v_lshlrev_b32_e32 v87, 11, v154
	v_lshlrev_b32_e32 v88, 11, v155
	v_lshlrev_b32_e32 v89, 11, v156
	v_lshlrev_b32_e32 v90, 11, v157
	v_lshlrev_b32_e32 v91, 11, v158
	v_lshlrev_b32_e32 v92, 11, v159
	v_lshlrev_b32_e32 v93, 11, v160
	v_lshlrev_b32_e32 v94, 11, v161
	v_and_b32_e32 v95, 24, v95
	s_movk_i32 s0, 0xffe0
	v_add_u32_e32 v162, 0x10000, v1
	v_add_u32_e32 v163, 0x12000, v1
	v_add_u32_e32 v164, 0x14000, v1
	v_add_u32_e32 v165, 0x16000, v1
	v_add_u32_e32 v166, 0x18000, v1
	v_add_u32_e32 v167, 0x1a000, v1
	v_add_u32_e32 v168, 0x1c000, v1
	v_add_u32_e32 v169, 0x1e000, v1
	v_and_or_b32 v170, v80, s0, v95
	v_lshlrev_b32_e32 v171, 2, v204
	v_lshlrev_b32_e32 v80, 2, v64
	v_add_u32_e32 v172, v65, v62
	v_add_u32_e32 v173, v65, v63
	v_add_u32_e32 v174, v65, v81
	v_add_u32_e32 v175, v65, v82
	v_add_u32_e32 v176, v65, v83
	v_add_u32_e32 v177, v65, v84
	v_add_u32_e32 v178, v65, v85
	v_add_u32_e32 v179, v65, v86
	v_add_u32_e32 v180, v65, v87
	v_add_u32_e32 v181, v65, v88
	v_add_u32_e32 v182, v65, v89
	v_add_u32_e32 v183, v65, v90
	v_add_u32_e32 v184, v65, v91
	v_add_u32_e32 v185, v65, v92
	v_add_u32_e32 v186, v65, v93
	v_add_u32_e32 v187, v65, v94
	s_mov_b32 s14, s90

; __device__ __forceinline__ float sigm(float x) { return __builtin_amdgcn_rcpf(1.0f + __builtin_amdgcn_exp2f(-LOG2E * x)); }
; __device__ __forceinline__ unsigned pk2(float lo, float hi) { return pg8::cvt_pk_bf16(lo, hi); }
; __device__ __forceinline__ void conv_phase(LAS unsigned char* lds, const bf16* U, const float* state, const float* wdw, const float* bdw, const float* lng, const float* lnb, bf16* Z, int blk, int nblk, int tid) {
;     ...
; #pragma unroll 8
;         for (int t = 0; t < 8 * ng; ++t) { const f32x2 st = stat[t]; const unsigned v = tile[t * 512 + tid]; const float y0 = __uint_as_float(v << 16), y1 = __uint_as_float(v & 0xffff0000u);
;             const float a0 = (y0 - st[0]) * st[1] * gg[0] + bb[0], a1 = (y1 - st[0]) * st[1] * gg[1] + bb[1];
;             *(unsigned*)(Z + (size_t)(t0 + t) * 1024 + c0) = pk2(a0 * pg8::sigm(a0), a1 * pg8::sigm(a1)); }
.LBB0_204:
	v_mul_u32_u24_e32 v226, 12, v204
	v_mov_b32_e32 v227, 0
	v_lshl_add_u64 v[226:227], v[78:79], 0, v[226:227]
	s_add_i32 s4, s2, -7
	s_ashr_i32 s5, s4, 31
	s_lshl_b64 s[4:5], s[4:5], 11
	v_lshl_add_u64 v[226:227], v[226:227], 0, s[4:5]
	v_lshrrev_b32_e32 v228, 7, v204
	s_mov_b32 s3, 0x20000
	v_lshl_add_u32 v228, v228, 3, s3
	v_mov_b32_e32 v229, v1
	s_mov_b32 s1, 0
	s_mov_b64 s[4:5], 0x2000
.Lconv_norm:
	ds_read_b128 v[62:65], v229
	ds_read_b64 v[242:243], v228
	s_waitcnt lgkmcnt(0)
	v_lshlrev_b32_e32 v81, 16, v62
	v_and_b32_e32 v82, 0xffff0000, v62
	v_lshlrev_b32_e32 v248, 16, v63
	v_and_b32_e32 v249, 0xffff0000, v63
	v_sub_f32_e32 v81, v81, v242
	v_sub_f32_e32 v82, v82, v242
	v_sub_f32_e32 v248, v248, v242
	v_sub_f32_e32 v249, v249, v242
	v_mul_f32_e32 v81, v243, v81
	v_mul_f32_e32 v82, v243, v82
	v_mul_f32_e32 v248, v243, v248
	v_mul_f32_e32 v249, v243, v249
	v_fma_f32 v81, v210, v81, v218
	v_fma_f32 v82, v211, v82, v219
	v_fma_f32 v248, v212, v248, v220
	v_fma_f32 v249, v213, v249, v221
	v_mul_f32_e32 v236, 0xbfb8aa3b, v81
	v_mul_f32_e32 v237, 0xbfb8aa3b, v82
	v_mul_f32_e32 v62, 0xbfb8aa3b, v248
	v_mul_f32_e32 v63, 0xbfb8aa3b, v249
	v_exp_f32_e32 v236, v236
	v_exp_f32_e32 v237, v237
	v_exp_f32_e32 v62, v62
	v_exp_f32_e32 v63, v63
	s_nop 0
	v_add_f32_e32 v236, 1.0, v236
	v_add_f32_e32 v237, 1.0, v237
	v_add_f32_e32 v62, 1.0, v62
	v_add_f32_e32 v63, 1.0, v63
	v_rcp_f32_e32 v236, v236
	v_rcp_f32_e32 v237, v237
	v_rcp_f32_e32 v62, v62
	v_rcp_f32_e32 v63, v63
	s_nop 0
	v_mul_f32_e32 v81, v81, v236
	v_mul_f32_e32 v82, v82, v237
	v_mul_f32_e32 v248, v248, v62
	v_mul_f32_e32 v249, v249, v63
	v_cvt_pk_bf16_f32 v244, v81, v82
	v_cvt_pk_bf16_f32 v245, v248, v249
	v_lshlrev_b32_e32 v81, 16, v64
	v_and_b32_e32 v82, 0xffff0000, v64
	v_lshlrev_b32_e32 v248, 16, v65
	v_and_b32_e32 v249, 0xffff0000, v65
	v_sub_f32_e32 v81, v81, v242
	v_sub_f32_e32 v82, v82, v242
	v_sub_f32_e32 v248, v248, v242
	v_sub_f32_e32 v249, v249, v242
	v_mul_f32_e32 v81, v243, v81
	v_mul_f32_e32 v82, v243, v82
	v_mul_f32_e32 v248, v243, v248
	v_mul_f32_e32 v249, v243, v249
	v_fma_f32 v81, v214, v81, v222
	v_fma_f32 v82, v215, v82, v223
	v_fma_f32 v248, v216, v248, v224
	v_fma_f32 v249, v217, v249, v225
	v_mul_f32_e32 v236, 0xbfb8aa3b, v81
	v_mul_f32_e32 v237, 0xbfb8aa3b, v82
	v_mul_f32_e32 v64, 0xbfb8aa3b, v248
	v_mul_f32_e32 v65, 0xbfb8aa3b, v249
	v_exp_f32_e32 v236, v236
	v_exp_f32_e32 v237, v237
	v_exp_f32_e32 v64, v64
	v_exp_f32_e32 v65, v65
	s_nop 0
	v_add_f32_e32 v236, 1.0, v236
	v_add_f32_e32 v237, 1.0, v237
	v_add_f32_e32 v64, 1.0, v64
	v_add_f32_e32 v65, 1.0, v65
	v_rcp_f32_e32 v236, v236
	v_rcp_f32_e32 v237, v237
	v_rcp_f32_e32 v64, v64
	v_rcp_f32_e32 v65, v65
	s_nop 0
	v_mul_f32_e32 v81, v81, v236
	v_mul_f32_e32 v82, v82, v237
	v_mul_f32_e32 v248, v248, v64
	v_mul_f32_e32 v249, v249, v65
	v_cvt_pk_bf16_f32 v246, v81, v82
	v_cvt_pk_bf16_f32 v247, v248, v249
	global_store_dwordx4 v[226:227], v[244:247], off
	v_add_u32_e32 v229, 0x2000, v229
	v_add_u32_e32 v228, 32, v228
	v_lshl_add_u64 v[226:227], v[226:227], 0, s[4:5]
	s_add_i32 s1, s1, 32
	s_cmp_lt_u32 s1, s0
	s_cbranch_scc1 .Lconv_norm
	s_add_i32 s14, s14, s98
	s_cmpk_gt_i32 s14, 0x43f
	s_barrier
	s_cbranch_scc0 .LBB0_79
